# code-phase test: +4 bytes for everything before the MLA unit (row pass, mid, conversion, barrier code), MLA phase kept
# speedup vs baseline: 1.0088x; 1.0013x over previous
; #define LAS __attribute__((address_space(3)))
; __device__ __forceinline__ unsigned xb_add(unsigned* p, unsigned v) { return __hip_atomic_fetch_add(p, v, __ATOMIC_RELAXED, __HIP_MEMORY_SCOPE_AGENT); }
; __device__ __forceinline__ unsigned xb_xcc_id() { return (unsigned)__builtin_amdgcn_s_getreg((3 << 11) | 20) & 0xFu; }
; __device__ __forceinline__ XcdBarrier xcd_barrier_post(unsigned* bar, volatile LAS unsigned* st) {
;     XcdBarrier b; b.bar = bar; b.x = xb_xcc_id(); b.st = st;
;     if (threadIdx.x == 0) (void)xb_add(&bar[XB_XCNT(b.x)], 1u);
;     return b;
; __global__ void __launch_bounds__(NWAVES * 64, 2) fwd_mega(Args args) {
;     extern __shared__ __attribute__((aligned(16))) unsigned char lds[];
;     cg::grid_group grid = cg::this_grid();
;     XcdBarrier bar; bar.bar = (unsigned*)args.ws; bar.x = 0; bar.st = nullptr;
;     if (args.ph_hi - args.ph_lo > 2) {
;         volatile LAS unsigned* MISC = (volatile LAS unsigned*)((LAS unsigned char*)lds + LDS_BYTES - 128);
;         if (threadIdx.x < 32) MISC[threadIdx.x] = 0u;
;         __syncthreads();
;         bar = xcd_barrier_post((unsigned*)args.ws, MISC + 8);
;     }
_Z8fwd_mega4Args:
	s_load_dwordx4 s[48:51], s[0:1], 0x68
	s_mov_b64 s[24:25], s[0:1]
	s_nop 0
	s_add_u32 s0, s24, 0x78
	s_load_dwordx2 s[66:67], s[24:25], 0x78
	s_addc_u32 s1, s25, 0
	s_mov_b32 s3, 0
	v_writelane_b32 v253, s0, 0
	s_nop 1
	v_writelane_b32 v253, s1, 1
	s_waitcnt lgkmcnt(0)
	s_sub_i32 s0, s51, s50
	s_mov_b32 s1, 0
	v_writelane_b32 v253, s1, 2
	s_cmp_lt_i32 s0, 3
	s_cbranch_scc1 .LBB0_7
	v_and_b32_e32 v1, 0x3ff, v0
	v_cmp_gt_u32_e32 vcc, 32, v1
	s_and_saveexec_b64 s[0:1], vcc
	v_lshl_add_u32 v2, v1, 2, 0
	v_add_u32_e32 v2, 0x23f80, v2
	v_mov_b32_e32 v3, 0
	ds_write_b32 v2, v3
	s_or_b64 exec, exec, s[0:1]
	s_waitcnt lgkmcnt(0)
	s_barrier
	s_getreg_b32 s0, hwreg(HW_REG_XCC_ID, 0, 4)
	s_and_b32 s3, s0, 15
	v_cmp_eq_u32_e32 vcc, 0, v1
	s_and_saveexec_b64 s[0:1], vcc
	s_cbranch_execz .LBB0_6
	s_mov_b64 s[4:5], exec
	v_mbcnt_lo_u32_b32 v1, s4, 0
	v_mbcnt_hi_u32_b32 v1, s5, v1
	v_cmp_eq_u32_e32 vcc, 0, v1
	s_and_b64 s[6:7], exec, vcc
	s_mov_b64 exec, s[6:7]
	s_cbranch_execz .LBB0_6
	s_lshl_b32 s6, s3, 8
	s_bcnt1_i32_b64 s4, s[4:5]
	v_mov_b32_e32 v1, s6
	v_mov_b32_e32 v2, s4
	global_atomic_add v1, v2, s[48:49] offset:1024

; __device__ __forceinline__ int opaque_tid() { int t = threadIdx.x; asm volatile("" : "+v"(t)); return t; }
; #define DMA_K(t, slot) do { const bf16_t* s_ = Knp + (long)(t) * (KVBLK * LDK); const unsigned d_ = (unsigned)__builtin_amdgcn_readfirstlane(kn_dst + (slot) * SHM_KN); \
;     glds16s(s_, kn_off, d_); glds16s(s_ + 16 * LDK, kn_off, d_ + 4096); glds16s(Krp + (long)(t) * (KVBLK * 64), kr_off, (unsigned)__builtin_amdgcn_readfirstlane(kr_dst + (slot) * SHM_KR)); } while (0)
; #define DMA_V(t, slot) do { const bf16_t* s_ = Vp + (long)(t) * (KVBLK * LDK); const unsigned d_ = (unsigned)__builtin_amdgcn_readfirstlane(v_dst + (slot) * SHM_V); \
;     glds16s(s_, v_off, d_); glds16s(s_ + 32 * LDK, v_off, d_ + 8192); } while (0)
; __device__ __forceinline__ void mla_unit(char* lds, const bf16_t* __restrict__ Qp, const bf16_t* __restrict__ Knp, const bf16_t* __restrict__ Vp, ...
;     ...
;   const int tid = opaque_tid(), wid = __builtin_amdgcn_readfirstlane(tid >> 6), lane = tid & 63, r32 = lane & 31, hi = lane >> 5;
;   float* wsf = (float*)(lds + P_WS) + wid * 64; float* li_l = wsf; float* al_l = wsf + 32;
;   const unsigned lds0 = (unsigned)(uintptr_t)lds;
;   const int pk = (wid & 3) + 8 * (wid >> 2);
;   const int krow_n = 4 * pk + (lane >> 4);
;   const unsigned kn_off = (unsigned)(krow_n * LDK + (((lane & 15) ^ (krow_n & 15)) << 3)) * 2u;
;   const int krow_r = 8 * wid + (lane >> 3);
;   const unsigned kr_off = (unsigned)(krow_r * 64 + (((lane & 7) ^ ((krow_r >> 1) & 7)) << 3)) * 2u;
;   const int vst_ = 2 * wid + (lane >> 5), vkk = (vst_ >> 2) * 8 + ((lane >> 2) & 7), vkey = (vkk & ~0xC) | ((vkk & 4) << 1) | ((vkk & 8) >> 1), vcol = (vst_ & 3) * 32 + (lane & 3) * 8;
;   const unsigned v_off = (unsigned)(vkey * LDK + vcol) * 2u;
;   const unsigned kn_dst = lds0 + P_KN + pk * 1024, kr_dst = lds0 + P_KR + wid * 1024, v_dst = lds0 + P_V + wid * 1024;
;     ...
;   if (first) { DMA_K(0, 0); DMA_V(0, 0); DMA_K(1, 1); DMA_V(1, 1); DMA_K(2, 2); }
.Lmla_prio_skip:
	s_nop 0
	s_ashr_i32 s5, s0, 5
	s_and_b32 s1, s8, 3
	s_and_b32 s5, s5, -8
	s_or_b32 s1, s1, s5
	s_lshl_b32 s5, s1, 2
	s_ashr_i32 s12, s0, 4
	v_bfe_u32 v1, v50, 4, 2
	s_ashr_i32 s7, s6, 31
	s_and_b32 s13, s12, 0x7ffff0
	s_lshr_b32 s12, s12, 1
	v_or_b32_e32 v2, s5, v1
	v_bitop3_b32 v1, s5, v50, v1 bitop3:0x36
	s_bfe_u32 s38, s74, 0x40005
	s_lshl_b64 s[30:31], s[6:7], 22
	s_lshl_b64 s[36:37], s[6:7], 20
	s_lshl_b32 s9, s8, 1
	s_and_b32 s12, s12, 4
	s_lshl_b32 s72, s1, 10
	v_lshlrev_b32_e32 v2, 9, v2
	v_lshlrev_b32_e32 v1, 4, v1
	s_cmp_lg_u32 0, -1
	v_and_or_b32 v197, v1, s53, v2
	v_bfe_u32 v1, v50, 3, 3
	s_cselect_b32 s1, 0, 0
	s_lshl_b32 s71, s8, 10
	v_lshl_or_b32 v1, s8, 3, v1
	s_add_i32 s14, s1, s72
	s_add_i32 s73, s71, s1
	v_lshlrev_b32_e32 v2, 7, v1
	v_lshrrev_b32_e32 v1, 1, v1
	s_add_i32 s76, s14, 0xc000
	s_add_i32 s75, s73, 0x18000
	v_readlane_b32 s1, v253, 3
	v_xor_b32_e32 v1, v1, v50
	s_cmp_lg_u32 s74, s1
	v_lshlrev_b32_e32 v1, 4, v1
	s_movk_i32 s1, 0x70
	v_and_or_b32 v198, v1, s1, v2
	v_lshrrev_b32_e32 v1, 2, v50
	v_lshrrev_b32_e32 v2, 1, v50
	v_bfe_u32 v49, v50, 5, 1
	v_and_or_b32 v1, v1, 3, s13
	v_and_b32_e32 v2, 8, v2
	v_lshlrev_b32_e32 v48, 4, v50
	v_or3_b32 v1, v1, v2, s12
	v_and_or_b32 v2, s9, 2, v49
	v_and_b32_e32 v3, 48, v48
	v_lshl_or_b32 v2, v2, 6, v3
	v_lshl_or_b32 v199, v1, 9, v2
	s_cbranch_scc1 .LBB0_238
	s_lshl_b32 s1, s38, 23
	v_readlane_b32 s5, v254, 62
	s_add_u32 s1, s5, s1
	v_readlane_b32 s5, v254, 63
	s_addc_u32 s5, s5, 0
	s_add_u32 s12, s1, s30
	s_addc_u32 s13, s5, s31
	s_add_u32 s14, s12, 0x100
	s_addc_u32 s15, s13, 0
	s_add_u32 s16, s26, s36
	s_addc_u32 s17, s27, s37
	s_mov_b32 m0, s76
	s_nop 0
	global_load_lds_dwordx4 v197, s[12:13]
	s_add_u32 s18, s12, 0x2000
	s_addc_u32 s19, s13, 0
	s_add_i32 s1, s76, 0x1000
	s_mov_b32 m0, s1
	s_nop 0
	global_load_lds_dwordx4 v197, s[18:19]
	s_mov_b32 m0, s75
	s_nop 0
	global_load_lds_dwordx4 v198, s[16:17]
	s_nop 0
	s_mov_b32 m0, s73
	s_nop 0
	global_load_lds_dwordx4 v199, s[14:15]
	s_add_u32 s14, s12, 0x4100
	s_addc_u32 s15, s13, 0
	s_add_i32 s1, s73, 0x2000
	s_mov_b32 m0, s1
	s_nop 0
	global_load_lds_dwordx4 v199, s[14:15]
	s_add_u32 s14, s12, 0x8000
	s_addc_u32 s15, s13, 0
	s_cmp_lg_u32 0, -1
	s_cselect_b32 s1, 0, 0
	s_add_i32 s5, s1, s72
	s_add_i32 s9, s5, 0x10000
	s_mov_b32 m0, s9
	s_nop 0
	global_load_lds_dwordx4 v197, s[14:15]
	s_add_u32 s14, s12, 0xa000
	s_addc_u32 s15, s13, 0
	s_add_i32 s9, s5, 0x11000
	s_mov_b32 m0, s9
	s_nop 0
	global_load_lds_dwordx4 v197, s[14:15]
	s_add_u32 s14, s16, 0x2000
	s_addc_u32 s15, s17, 0
	s_add_i32 s1, s1, s71
	s_add_i32 s9, s1, 0x1a000
	s_mov_b32 m0, s9
	s_nop 0
	global_load_lds_dwordx4 v198, s[14:15]
	s_add_u32 s14, s12, 0x8100
	s_addc_u32 s15, s13, 0
	s_add_i32 s9, s1, 0x4000
	s_mov_b32 m0, s9
	s_nop 0
	global_load_lds_dwordx4 v199, s[14:15]
	s_add_u32 s14, s12, 0xc100
	s_addc_u32 s15, s13, 0
	s_add_i32 s9, s1, 0x6000
	s_mov_b32 m0, s9
	s_nop 0
	global_load_lds_dwordx4 v199, s[14:15]
	s_add_u32 s14, s12, 0x10000
	s_addc_u32 s15, s13, 0
	s_add_i32 s9, s5, 0x14000
	s_add_u32 s12, s12, 0x12000
	s_mov_b32 m0, s9
	s_nop 0
	global_load_lds_dwordx4 v197, s[14:15]
	s_addc_u32 s13, s13, 0
	s_add_i32 s5, s5, 0x15000
	s_mov_b32 m0, s5
	s_nop 0
	global_load_lds_dwordx4 v197, s[12:13]
	s_add_u32 s12, s16, 0x4000
	s_addc_u32 s13, s17, 0
	s_add_i32 s1, s1, 0x1c000
	s_mov_b32 m0, s1
	s_nop 0
	global_load_lds_dwordx4 v198, s[12:13]
